# v11 + prep: one wait for all three tokens' loads; attention item prologues: Q tile loads issued back to back before the LDS writes
# baseline (speedup 1.0000x reference)
.LBB0_1173:
	s_or_b64 exec, exec, s[22:23]
	s_waitcnt vmcnt(0)
	v_lshlrev_b32_e32 v86, 16, v86
	v_lshlrev_b32_e32 v87, 16, v87
	v_lshlrev_b32_e32 v82, 16, v82
	v_lshlrev_b32_e32 v83, 16, v83
	v_lshlrev_b32_e32 v78, 16, v78
	v_lshlrev_b32_e32 v79, 16, v79
	v_lshlrev_b32_e32 v76, 16, v76
	v_lshlrev_b32_e32 v77, 16, v77
	v_lshlrev_b32_e32 v74, 16, v74
	v_lshlrev_b32_e32 v75, 16, v75
	v_lshlrev_b32_e32 v72, 16, v72
	v_lshlrev_b32_e32 v73, 16, v73
	v_lshlrev_b32_e32 v70, 16, v70
	v_lshlrev_b32_e32 v71, 16, v71
	v_lshlrev_b32_e32 v68, 16, v68
	v_lshlrev_b32_e32 v69, 16, v69
	v_lshlrev_b32_e32 v208, 16, v208
	v_lshlrev_b32_e32 v211, 16, v211
	v_lshlrev_b32_e32 v209, 16, v209
	v_lshlrev_b32_e32 v214, 16, v214
	v_lshlrev_b32_e32 v210, 16, v210
	v_lshlrev_b32_e32 v216, 16, v216
	v_lshlrev_b32_e32 v213, 16, v213
	v_lshlrev_b32_e32 v219, 16, v219
	s_and_saveexec_b64 s[14:15], vcc
	s_xor_b64 s[14:15], exec, s[14:15]
	s_cbranch_execz .LBB0_1177
	v_bfe_u32 v39, v42, 6, 6
	v_cvt_f32_ubyte0_e32 v59, v39
	v_and_b32_e32 v39, 63, v42
	v_cvt_f32_ubyte0_e32 v61, v39
	v_cndmask_b32_e64 v39, v61, v59, s[2:3]
	v_mul_f32_e32 v39, v110, v39
	v_mul_f32_e32 v39, 0.15915494, v39
	v_sin_f32_e32 v63, v39
	v_cos_f32_e32 v39, v39
	s_waitcnt vmcnt(17)
	v_lshlrev_b32_e32 v95, 16, v232
	v_lshlrev_b32_e32 v94, 16, v231
	v_mul_f32_e32 v188, v63, v95
	v_fma_f32 v188, v39, v94, -v188
	v_mul_f32_e32 v39, v39, v95
	v_fmac_f32_e32 v39, v63, v94
	v_bfe_u32 v63, v39, 16, 1
	v_bfe_u32 v189, v188, 16, 1
	v_add3_u32 v39, v39, v63, s42
	v_add3_u32 v188, v188, v189, s42
	global_store_short_d16_hi v[92:93], v39, off offset:544
	v_mov_b32_e32 v39, 0
	global_store_short_d16_hi v[92:93], v188, off offset:512
	s_and_saveexec_b64 s[16:17], s[4:5]
	s_cbranch_execz .LBB0_1176
	v_cndmask_b32_e64 v39, v61, v59, s[6:7]
	v_mul_f32_e32 v39, v111, v39
	v_mul_f32_e32 v39, 0.15915494, v39
	v_sin_f32_e32 v92, v39
	v_cos_f32_e32 v94, v39
	s_waitcnt vmcnt(17)
	v_lshlrev_b32_e32 v189, 16, v230
	v_lshlrev_b32_e32 v188, 16, v229
	v_pk_mul_f32 v[92:93], v[92:93], v[188:189] op_sel:[0,1] op_sel_hi:[0,0]
	v_pk_fma_f32 v[230:231], v[94:95], v[188:189], v[92:93] neg_lo:[0,0,1] neg_hi:[0,0,1]
	v_pk_fma_f32 v[92:93], v[94:95], v[188:189], v[92:93] op_sel_hi:[0,1,1]
	v_and_b32_sdwa v39, v93, v182 dst_sel:DWORD dst_unused:UNUSED_PAD src0_sel:WORD_1 src1_sel:DWORD
	v_and_b32_sdwa v59, v230, v182 dst_sel:DWORD dst_unused:UNUSED_PAD src0_sel:WORD_1 src1_sel:DWORD
	v_add3_u32 v39, v93, v39, s42
	v_add3_u32 v59, v230, v59, s42
	global_store_short_d16_hi v[90:91], v59, off offset:2336
	global_store_short_d16_hi v[90:91], v39, off offset:2352
	v_and_b32_e32 v91, 0xffff0000, v39
	v_and_b32_e32 v90, 0xffff0000, v59
	v_pk_mul_f32 v[90:91], v[90:91], v[90:91]
	s_nop 0
	v_add_f32_e32 v39, v90, v91

.LBB0_1405:
	s_or_b64 exec, exec, s[2:3]
	v_mov_b32_e32 v133, v199
	s_waitcnt lgkmcnt(0)
	s_barrier
	flat_load_dword v0, v[132:133] sc0 sc1
	s_waitcnt vmcnt(0)
	s_mov_b64 s[2:3], -1
	s_waitcnt lgkmcnt(0)
	v_cmp_gt_i32_e32 vcc, 64, v0
	s_and_saveexec_b64 s[30:31], vcc
	s_cbranch_execz .LBB0_1400
	v_lshl_add_u32 v0, v0, 1, v204
	v_ashrrev_i32_e32 v1, 5, v0
	v_add_u32_e32 v2, s52, v1
	v_lshlrev_b32_e32 v0, 7, v0
	v_and_b32_e32 v4, 0xf80, v0
	v_and_b32_e32 v0, -4, v2
	v_and_b32_e32 v117, 3, v1
	v_ashrrev_i32_e32 v1, 31, v0
	v_lshl_add_u64 v[0:1], v[0:1], 2, s[22:23]
	v_lshlrev_b32_e32 v128, 2, v117
	v_mov_b32_e32 v101, v131
	v_lshl_add_u64 v[0:1], v[0:1], 0, v[128:129]
	global_load_dword v8, v[0:1], off sc1
	global_load_dword v9, v129, s[24:25] offset:256 sc1
	v_and_b32_e32 v148, 0xff, v101
	v_mul_u32_u24_e32 v0, 0x60, v117
	v_ashrrev_i32_e32 v24, 2, v2
	v_lshlrev_b32_e32 v128, 1, v0
	v_mul_lo_u16_e32 v0, 0xab, v148
	v_lshlrev_b32_e32 v124, 12, v24
	v_lshrrev_b16_e32 v208, 11, v0
	v_or_b32_e32 v116, v124, v4
	v_mad_i32_i24 v25, v208, -12, v148
	v_lshl_add_u64 v[6:7], s[84:85], 0, v[128:129]
	v_or_b32_e32 v0, v116, v208
	s_movk_i32 s4, 0x300
	v_lshlrev_b32_e32 v118, 3, v25
	v_mad_i64_i32 v[0:1], s[2:3], v0, s4, v[6:7]
	v_ashrrev_i32_e32 v119, 31, v118
	v_lshl_add_u64 v[0:1], v[118:119], 1, v[0:1]
	s_barrier
	global_load_dwordx4 v[216:219], v[0:1], off
	v_mul_u32_u24_e32 v5, 0x68, v208
	v_lshlrev_b32_e32 v211, 1, v5
	v_lshlrev_b32_e32 v5, 4, v25
	v_add3_u32 v146, s33, v211, v5
	s_mov_b32 s5, 0x7060302
	v_lshlrev_b32_e32 v105, 1, v148
	s_mov_b32 s12, 0
	s_mov_b64 s[8:9], 0
	v_or_b32_e32 v0, 0x100, v148
	v_mul_u32_u24_e32 v1, 0x1556, v0
	v_lshrrev_b32_e32 v209, 16, v1
	v_mad_i32_i24 v28, v209, -12, v0
	v_or_b32_e32 v0, v116, v209
	v_lshlrev_b32_e32 v120, 3, v28
	v_mad_i64_i32 v[0:1], s[2:3], v0, s4, v[6:7]
	v_ashrrev_i32_e32 v121, 31, v120
	v_lshl_add_u64 v[0:1], v[120:121], 1, v[0:1]
	global_load_dwordx4 v[220:223], v[0:1], off
	v_mul_u32_u24_e32 v5, 0x68, v209
	v_lshlrev_b32_e32 v212, 1, v5
	v_lshlrev_b32_e32 v5, 4, v28
	v_add3_u32 v147, s33, v212, v5
	v_or_b32_e32 v5, 0x300, v148
	v_or_b32_e32 v0, 0x200, v148
	v_mul_u32_u24_e32 v1, 0x1556, v0
	v_lshrrev_b32_e32 v210, 16, v1
	v_mad_i32_i24 v32, v210, -12, v0
	v_mul_u32_u24_e32 v2, 0x1556, v5
	v_or_b32_e32 v0, v116, v210
	v_lshlrev_b32_e32 v122, 3, v32
	v_perm_b32 v10, v2, v1, s5
	v_mad_i64_i32 v[0:1], s[2:3], v0, s4, v[6:7]
	v_ashrrev_i32_e32 v123, 31, v122
	v_lshl_add_u64 v[0:1], v[122:123], 1, v[0:1]
	v_lshrrev_b32_e32 v149, 16, v2
	global_load_dwordx4 v[224:227], v[0:1], off
	s_mov_b32 s2, 0xd00068
	v_pk_mul_lo_u16 v10, v10, s2
	v_mad_i32_i24 v36, v149, -12, v5
	v_and_b32_e32 v213, 0xfff8, v10
	v_lshl_add_u32 v40, v213, 1, s33
	v_lshl_add_u32 v150, v32, 4, v40
	v_lshlrev_b32_e32 v44, 3, v36
	v_ashrrev_i32_e32 v45, 31, v44
	v_lshrrev_b32_e32 v5, 16, v10
	v_lshlrev_b32_e32 v10, 4, v36
	v_add3_u32 v151, s33, v5, v10
	v_or_b32_e32 v5, 0x500, v148
	v_or_b32_e32 v0, v116, v149
	v_mad_i64_i32 v[0:1], s[2:3], v0, s4, v[6:7]
	v_lshl_add_u64 v[0:1], v[44:45], 1, v[0:1]
	global_load_dwordx4 v[228:231], v[0:1], off
	v_or_b32_e32 v0, 0x400, v148
	v_mul_u32_u24_e32 v1, 0x1556, v0
	v_lshrrev_b32_e32 v152, 16, v1
	v_mad_i32_i24 v42, v152, -12, v0
	v_mul_u32_u24_e32 v2, 0x1556, v5
	v_or_b32_e32 v0, v116, v152
	v_lshlrev_b32_e32 v46, 3, v42
	v_perm_b32 v10, v2, v1, s5
	v_mad_i64_i32 v[0:1], s[2:3], v0, s4, v[6:7]
	v_ashrrev_i32_e32 v47, 31, v46
	v_lshl_add_u64 v[0:1], v[46:47], 1, v[0:1]
	v_lshrrev_b32_e32 v153, 16, v2
	global_load_dwordx4 v[232:235], v[0:1], off
	s_movk_i32 s2, 0xd0
	v_pk_mul_lo_u16 v10, v10, s2 op_sel_hi:[1,0]
	v_lshlrev_b32_e32 v12, 4, v42
	v_and_b32_e32 v11, 0xfff0, v10
	v_add3_u32 v154, s33, v11, v12
	v_mad_i32_i24 v48, v153, -12, v5
	v_lshlrev_b32_e32 v102, 3, v48
	v_ashrrev_i32_e32 v103, 31, v102
	v_add_u32_sdwa v106, s33, v10 dst_sel:DWORD dst_unused:UNUSED_PAD src0_sel:DWORD src1_sel:WORD_1
	v_lshl_add_u32 v5, v48, 4, v106
	v_or_b32_e32 v0, v116, v153
	v_mad_i64_i32 v[0:1], s[2:3], v0, s4, v[6:7]
	v_lshl_add_u64 v[0:1], v[102:103], 1, v[0:1]
	global_load_dwordx4 v[236:239], v[0:1], off
	v_readlane_b32 s2, v254, 15
	v_mov_b32_e32 v7, v148
	s_waitcnt vmcnt(0)
	ds_write_b128 v146, v[216:219]
	ds_write_b128 v147, v[220:223]
	ds_write_b128 v150, v[224:227]
	ds_write_b128 v151, v[228:231]
	ds_write_b128 v154, v[232:235]
	ds_write_b128 v5, v[236:239]
	v_sub_u32_e32 v0, 0x47f, v148
	v_lshrrev_b32_e32 v0, 8, v0
	v_add_u32_e32 v1, 4, v0
	v_and_b32_e32 v5, 12, v1
	v_mov_b32_e32 v1, v0
	v_mov_b32_e32 v2, v0
	v_mov_b32_e32 v3, v0
	v_add_u32_e32 v6, s2, v105
	s_branch .LBB0_1408

.LBB0_1520:
	s_or_b64 exec, exec, s[0:1]
	v_mov_b32_e32 v133, v199
	s_waitcnt lgkmcnt(0)
	s_barrier
	flat_load_dword v0, v[132:133] sc0 sc1
	s_waitcnt vmcnt(0)
	v_readlane_b32 s0, v254, 41
	s_waitcnt lgkmcnt(0)
	v_lshlrev_b32_e32 v18, 1, v0
	v_add_u32_e32 v48, v150, v18
	v_cmp_gt_i32_e32 vcc, s0, v48
	s_mov_b64 s[0:1], -1
	s_mov_b64 s[2:3], exec
	v_writelane_b32 v254, s2, 47
	s_nop 1
	v_writelane_b32 v254, s3, 48
	s_and_b64 s[2:3], s[2:3], vcc
	s_mov_b64 exec, s[2:3]
	s_cbranch_execz .LBB0_1515
	v_readlane_b32 s0, v254, 37
	s_nop 1
	v_cmp_le_i32_e32 vcc, s0, v48
	s_and_saveexec_b64 s[0:1], vcc
	s_xor_b64 s[0:1], exec, s[0:1]
	v_writelane_b32 v254, s0, 49
	s_nop 1
	v_writelane_b32 v254, s1, 50
	s_cbranch_execz .LBB0_1703
	v_readlane_b32 s0, v254, 39
	s_nop 1
	v_cmp_le_i32_e32 vcc, s0, v48
	s_and_saveexec_b64 s[0:1], vcc
	s_xor_b64 s[0:1], exec, s[0:1]
	v_writelane_b32 v254, s0, 51
	s_nop 1
	v_writelane_b32 v254, s1, 52
	s_cbranch_execz .LBB0_1693
	v_readlane_b32 s0, v254, 38
	s_nop 1
	v_cmp_le_i32_e32 vcc, s0, v48
	s_and_saveexec_b64 s[0:1], vcc
	s_xor_b64 s[6:7], exec, s[0:1]
	s_cbranch_execz .LBB0_1541
	v_readlane_b32 s0, v254, 40
	v_bfe_u32 v88, v48, 1, 2
	v_lshlrev_b32_e32 v128, 6, v88
	v_cmp_le_i32_e32 vcc, s0, v48
	s_and_saveexec_b64 s[0:1], vcc
	s_xor_b64 s[0:1], exec, s[0:1]
	s_cbranch_execz .LBB0_1534
	v_readlane_b32 s2, v254, 40
	v_mov_b32_e32 v12, v131
	v_lshlrev_b32_e32 v84, 1, v128
	v_subrev_u32_e32 v1, s2, v48
	v_lshlrev_b32_e32 v1, 5, v1
	v_and_b32_e32 v13, 0x7fffff00, v1
	v_mov_b32_e32 v85, v129
	v_lshlrev_b32_e32 v1, 4, v12
	v_add_u32_e32 v14, 0x8000, v13
	v_lshl_add_u64 v[8:9], s[82:83], 0, v[84:85]
	v_and_b32_e32 v6, 0x70, v1
	v_mov_b32_e32 v7, v129
	v_or_b32_e32 v116, v14, v151
	v_lshl_add_u64 v[10:11], v[8:9], 0, v[6:7]
	v_bfe_u32 v7, v12, 3, 5
	v_or_b32_e32 v16, v7, v116
	v_mov_b32_e32 v17, v129
	v_lshlrev_b64 v[2:3], 12, v[16:17]
	v_lshl_add_u64 v[2:3], v[10:11], 0, v[2:3]
	s_barrier
	global_load_dwordx4 v[216:219], v[2:3], off offset:2400
	v_add_u32_e32 v1, s33, v6
	v_mul_u32_u24_e32 v15, 0x48, v7
	v_lshl_add_u32 v85, v15, 1, v1
	v_or_b32_e32 v15, 32, v7
	v_or_b32_e32 v17, 64, v7
	s_movk_i32 s3, 0x90
	v_mad_u32_u24 v1, v17, s3, v1
	v_and_b32_e32 v0, 0xff, v12
	s_mov_b32 s2, 16
	s_mov_b32 s4, 0x3e38aa3b
	v_or_b32_e32 v2, v15, v116
	v_mov_b32_e32 v3, v129
	v_lshlrev_b64 v[2:3], 12, v[2:3]
	v_lshl_add_u64 v[2:3], v[10:11], 0, v[2:3]
	global_load_dwordx4 v[220:223], v[2:3], off offset:2400
	v_or_b32_e32 v2, v17, v116
	v_mov_b32_e32 v3, v129
	v_lshlrev_b64 v[2:3], 12, v[2:3]
	v_lshl_add_u64 v[2:3], v[10:11], 0, v[2:3]
	global_load_dwordx4 v[224:227], v[2:3], off offset:2400
	v_or_b32_e32 v2, 0x60, v16
	v_mov_b32_e32 v3, v129
	v_lshlrev_b64 v[2:3], 12, v[2:3]
	v_lshl_add_u64 v[2:3], v[10:11], 0, v[2:3]
	global_load_dwordx4 v[228:231], v[2:3], off offset:2400
	s_waitcnt vmcnt(0)
	ds_write_b128 v85, v[216:219]
	ds_write_b128 v85, v[220:223] offset:4608
	ds_write_b128 v1, v[224:227]
	ds_write_b128 v1, v[228:231] offset:4608
	v_or_b32_e32 v3, 0x300, v0
	v_or_b32_e32 v2, 0x200, v0
	v_or_b32_e32 v1, 0x100, v0
	v_mov_b64_e32 v[4:5], v[2:3]
	v_mov_b64_e32 v[2:3], v[0:1]
	s_waitcnt lgkmcnt(0)
	s_barrier

.LBB0_1534:
	s_or_saveexec_b64 s[8:9], s[0:1]
	v_mov_b64_e32 v[16:17], 0x620
	v_mov_b64_e32 v[14:15], 0x640
	v_mov_b64_e32 v[12:13], 0x660
	s_xor_b64 exec, exec, s[8:9]
	s_cbranch_execz .LBB0_1540
	v_readlane_b32 s0, v254, 38
	v_mov_b32_e32 v33, v131
	v_lshlrev_b32_e32 v80, 1, v128
	v_subrev_u32_e32 v1, s0, v48
	v_lshlrev_b32_e32 v1, 5, v1
	v_and_b32_e32 v32, 0xffffff00, v1
	v_add_u32_e32 v7, 0x8000, v32
	v_or_b32_e32 v90, v7, v151
	v_lshlrev_b32_e32 v1, 3, v33
	v_bfe_u32 v34, v33, 3, 5
	v_mov_b32_e32 v81, v129
	v_and_b32_e32 v6, 56, v1
	v_or_b32_e32 v8, v34, v90
	v_lshl_add_u64 v[2:3], s[82:83], 0, v[80:81]
	v_lshlrev_b32_e32 v4, 1, v6
	v_mov_b32_e32 v5, v129
	v_ashrrev_i32_e32 v9, 31, v8
	v_lshl_add_u64 v[10:11], v[2:3], 0, v[4:5]
	v_lshlrev_b64 v[2:3], 12, v[8:9]
	v_lshl_add_u64 v[2:3], v[10:11], 0, v[2:3]
	s_barrier
	v_add_u32_e32 v1, s33, v4
	global_load_dwordx4 v[216:219], v[2:3], off
	v_mul_u32_u24_e32 v9, 0x48, v34
	v_lshl_add_u32 v93, v9, 1, v1
	v_or_b32_e32 v9, 32, v34
	v_or_b32_e32 v12, 64, v34
	s_movk_i32 s1, 0x90
	v_mad_u32_u24 v1, v12, s1, v1
	v_and_b32_e32 v89, 15, v33
	v_and_b32_e32 v0, 0xff, v33
	s_mov_b32 s0, 16
	s_mov_b32 s4, 0x3e38aa3b
	v_or_b32_e32 v2, v9, v90
	v_ashrrev_i32_e32 v3, 31, v2
	v_lshlrev_b64 v[2:3], 12, v[2:3]
	v_lshl_add_u64 v[2:3], v[10:11], 0, v[2:3]
	global_load_dwordx4 v[220:223], v[2:3], off
	v_or_b32_e32 v2, v12, v90
	v_ashrrev_i32_e32 v3, 31, v2
	v_lshlrev_b64 v[2:3], 12, v[2:3]
	v_lshl_add_u64 v[2:3], v[10:11], 0, v[2:3]
	global_load_dwordx4 v[224:227], v[2:3], off
	v_or_b32_e32 v2, 0x60, v8
	v_ashrrev_i32_e32 v3, 31, v2
	v_lshlrev_b64 v[2:3], 12, v[2:3]
	v_lshl_add_u64 v[2:3], v[10:11], 0, v[2:3]
	global_load_dwordx4 v[228:231], v[2:3], off
	s_waitcnt vmcnt(0)
	ds_write_b128 v93, v[216:219]
	ds_write_b128 v93, v[220:223] offset:4608
	ds_write_b128 v1, v[224:227]
	ds_write_b128 v1, v[228:231] offset:4608
	v_lshlrev_b32_e32 v1, 2, v33
	v_and_b32_e32 v1, 64, v1
	v_lshlrev_b32_e32 v2, 1, v89
	v_add3_u32 v8, s33, v1, v2
	v_or_b32_e32 v3, 0x300, v0
	v_or_b32_e32 v2, 0x200, v0
	v_or_b32_e32 v1, 0x100, v0
	v_mov_b64_e32 v[4:5], v[2:3]
	s_waitcnt lgkmcnt(0)
	s_barrier
	v_mov_b64_e32 v[2:3], v[0:1]

.LBB0_1541:
	s_or_saveexec_b64 s[0:1], s[6:7]
	v_writelane_b32 v254, s0, 53
	s_nop 1
	v_writelane_b32 v254, s1, 54
	s_xor_b64 exec, exec, s[0:1]
	s_cbranch_execz .LBB0_1692
	v_readlane_b32 s0, v254, 39
	v_and_b32_e32 v8, 31, v48
	v_mov_b32_e32 v10, v131
	v_subrev_u32_e32 v0, s0, v48
	v_ashrrev_i32_e32 v9, 7, v0
	v_lshlrev_b32_e32 v97, 12, v9
	v_bfe_u32 v11, v0, 5, 2
	v_lshl_or_b32 v103, v8, 7, v97
	v_bfe_u32 v111, v10, 3, 5
	v_lshlrev_b32_e32 v2, 7, v11
	v_mov_b32_e32 v3, v129
	v_lshlrev_b32_e32 v1, 4, v10
	v_or_b32_e32 v12, v111, v103
	v_lshl_add_u64 v[6:7], s[82:83], 0, v[2:3]
	v_and_b32_e32 v2, 0x70, v1
	v_ashrrev_i32_e32 v13, 31, v12
	v_lshl_add_u64 v[98:99], v[6:7], 0, v[2:3]
	v_add_u32_e32 v1, s33, v2
	v_lshlrev_b64 v[2:3], 12, v[12:13]
	v_lshl_add_u64 v[2:3], v[98:99], 0, v[2:3]
	s_barrier
	global_load_dwordx4 v[216:219], v[2:3], off offset:2400
	v_mul_u32_u24_e32 v13, 0x48, v111
	v_lshl_add_u32 v110, v13, 1, v1
	v_or_b32_e32 v112, 32, v111
	v_or_b32_e32 v13, 64, v111
	s_movk_i32 s1, 0x90
	v_mad_u32_u24 v1, v13, s1, v1
	v_and_b32_e32 v0, 0xff, v10
	v_lshlrev_b32_e32 v128, 6, v11
	s_mov_b32 s0, 16
	s_mov_b32 s2, 0x3e38aa3b
	v_or_b32_e32 v2, v112, v103
	v_ashrrev_i32_e32 v3, 31, v2
	v_lshlrev_b64 v[2:3], 12, v[2:3]
	v_lshl_add_u64 v[2:3], v[98:99], 0, v[2:3]
	global_load_dwordx4 v[220:223], v[2:3], off offset:2400
	v_or_b32_e32 v2, v13, v103
	v_ashrrev_i32_e32 v3, 31, v2
	v_lshlrev_b64 v[2:3], 12, v[2:3]
	v_lshl_add_u64 v[2:3], v[98:99], 0, v[2:3]
	global_load_dwordx4 v[224:227], v[2:3], off offset:2400
	v_or_b32_e32 v2, 0x60, v12
	v_ashrrev_i32_e32 v3, 31, v2
	v_lshlrev_b64 v[2:3], 12, v[2:3]
	v_lshl_add_u64 v[2:3], v[98:99], 0, v[2:3]
	global_load_dwordx4 v[228:231], v[2:3], off offset:2400
	s_waitcnt vmcnt(0)
	ds_write_b128 v110, v[216:219]
	ds_write_b128 v110, v[220:223] offset:4608
	ds_write_b128 v1, v[224:227]
	ds_write_b128 v1, v[228:231] offset:4608
	v_or_b32_e32 v3, 0x300, v0
	v_or_b32_e32 v2, 0x200, v0
	v_or_b32_e32 v1, 0x100, v0
	v_mov_b64_e32 v[4:5], v[2:3]
	v_mov_b64_e32 v[2:3], v[0:1]
	s_waitcnt lgkmcnt(0)
	s_barrier

.LBB0_1693:
	v_readlane_b32 s0, v254, 51
	v_readlane_b32 s1, v254, 52
	s_andn2_saveexec_b64 s[28:29], s[0:1]
	s_cbranch_execz .LBB0_1702
	v_readlane_b32 s0, v254, 37
	v_and_b32_e32 v13, 31, v48
	v_mov_b32_e32 v25, v131
	v_subrev_u32_e32 v0, s0, v48
	v_ashrrev_i32_e32 v24, 7, v0
	v_lshlrev_b32_e32 v97, 12, v24
	v_lshlrev_b32_e32 v4, 7, v13
	v_bfe_u32 v95, v0, 5, 2
	v_or_b32_e32 v94, v97, v4
	v_lshlrev_b32_e32 v1, 3, v25
	v_bfe_u32 v102, v25, 3, 5
	v_lshlrev_b32_e32 v2, 7, v95
	v_mov_b32_e32 v3, v129
	v_and_b32_e32 v12, 56, v1
	v_or_b32_e32 v10, v102, v94
	v_lshl_add_u64 v[2:3], s[82:83], 0, v[2:3]
	v_lshlrev_b32_e32 v6, 1, v12
	v_mov_b32_e32 v7, v129
	v_ashrrev_i32_e32 v11, 31, v10
	v_lshl_add_u64 v[2:3], v[2:3], 0, v[6:7]
	v_add_u32_e32 v1, s33, v6
	v_lshlrev_b64 v[6:7], 12, v[10:11]
	v_lshl_add_u64 v[6:7], v[2:3], 0, v[6:7]
	s_barrier
	global_load_dwordx4 v[216:219], v[6:7], off
	v_mul_u32_u24_e32 v5, 0x48, v102
	v_lshl_add_u32 v101, v5, 1, v1
	v_or_b32_e32 v103, 32, v102
	v_or_b32_e32 v5, 64, v102
	s_movk_i32 s1, 0x90
	v_mad_u32_u24 v1, v5, s1, v1
	v_and_b32_e32 v93, 15, v25
	v_and_b32_e32 v0, 0xff, v25
	v_lshlrev_b32_e32 v128, 6, v95
	s_mov_b32 s0, 16
	s_mov_b32 s4, 0x3e38aa3b
	v_or_b32_e32 v6, v103, v94
	v_ashrrev_i32_e32 v7, 31, v6
	v_lshlrev_b64 v[6:7], 12, v[6:7]
	v_lshl_add_u64 v[6:7], v[2:3], 0, v[6:7]
	global_load_dwordx4 v[220:223], v[6:7], off
	v_or_b32_e32 v6, v5, v94
	v_ashrrev_i32_e32 v7, 31, v6
	v_lshlrev_b64 v[6:7], 12, v[6:7]
	v_lshl_add_u64 v[6:7], v[2:3], 0, v[6:7]
	global_load_dwordx4 v[224:227], v[6:7], off
	v_mov_b32_e32 v5, v4
	v_or_b32_e32 v6, 0x60, v10
	v_ashrrev_i32_e32 v7, 31, v6
	v_lshlrev_b64 v[6:7], 12, v[6:7]
	v_lshl_add_u64 v[2:3], v[2:3], 0, v[6:7]
	global_load_dwordx4 v[228:231], v[2:3], off
	v_lshlrev_b32_e32 v2, 1, v93
	v_or_b32_e32 v3, 0x300, v0
	s_waitcnt vmcnt(0)
	ds_write_b128 v101, v[216:219]
	ds_write_b128 v101, v[220:223] offset:4608
	ds_write_b128 v1, v[224:227]
	ds_write_b128 v1, v[228:231] offset:4608
	v_bfe_u32 v1, v25, 4, 1
	v_cmp_eq_u32_e32 vcc, 0, v1
	v_lshlrev_b32_e32 v1, 6, v1
	v_add3_u32 v14, s33, v1, v2
	v_cvt_f32_ubyte0_e32 v1, v93
	v_mul_f32_e32 v1, 0xbf549a78, v1
	v_exp_f32_e32 v16, v1
	v_or_b32_e32 v2, 0x200, v0
	v_or_b32_e32 v1, 0x100, v0
	v_mov_b64_e32 v[10:11], v[2:3]
	v_mov_b32_e32 v6, v4
	v_mov_b32_e32 v7, v4
	v_mov_b32_e32 v17, v16
	v_mov_b32_e32 v18, v16
	v_mov_b32_e32 v19, v16
	v_mov_b64_e32 v[8:9], v[0:1]
	s_waitcnt lgkmcnt(0)
	s_barrier

.LBB0_1703:
	v_readlane_b32 s0, v254, 49
	v_readlane_b32 s1, v254, 50
	s_andn2_saveexec_b64 s[8:9], s[0:1]
	s_cbranch_execz .LBB0_1514
	v_add_u32_e32 v0, v18, v204
	v_bfe_u32 v133, v0, 1, 2
	v_mov_b32_e32 v54, v131
	v_lshlrev_b32_e32 v0, 5, v0
	v_and_b32_e32 v52, 0xffffff00, v0
	v_and_b32_e32 v36, 0xff, v54
	v_mul_u32_u24_e32 v0, 0x60, v133
	v_lshlrev_b32_e32 v128, 1, v0
	v_mul_lo_u16_e32 v0, 0xab, v36
	v_add_u32_e32 v37, 0x8000, v52
	v_lshrrev_b16_e32 v53, 11, v0
	v_or_b32_e32 v152, v37, v151
	v_mad_i32_i24 v24, v53, -12, v36
	v_lshl_add_u64 v[4:5], s[84:85], 0, v[128:129]
	v_or_b32_e32 v0, v152, v53
	s_movk_i32 s2, 0x300
	s_waitcnt vmcnt(5)
	v_lshlrev_b32_e32 v44, 3, v24
	v_mad_i64_i32 v[0:1], s[0:1], v0, s2, v[4:5]
	v_ashrrev_i32_e32 v45, 31, v44
	v_lshl_add_u64 v[0:1], v[44:45], 1, v[0:1]
	s_barrier
	global_load_dwordx4 v[216:219], v[0:1], off
	v_mul_u32_u24_e32 v6, 0x68, v53
	v_lshlrev_b32_e32 v6, 1, v6
	v_lshlrev_b32_e32 v7, 4, v24
	v_add3_u32 v157, s33, v6, v7
	v_or_b32_e32 v6, 0x200, v36
	s_mov_b32 s3, 0x7060302
	v_or_b32_e32 v0, 0x100, v36
	v_mul_u32_u24_e32 v1, 0x1556, v0
	v_lshrrev_b32_e32 v55, 16, v1
	v_mad_i32_i24 v28, v55, -12, v0
	v_mul_u32_u24_e32 v2, 0x1556, v6
	v_or_b32_e32 v0, v152, v55
	v_lshlrev_b32_e32 v46, 3, v28
	v_perm_b32 v7, v2, v1, s3
	v_mad_i64_i32 v[0:1], s[0:1], v0, s2, v[4:5]
	v_ashrrev_i32_e32 v47, 31, v46
	v_lshl_add_u64 v[0:1], v[46:47], 1, v[0:1]
	v_lshrrev_b32_e32 v56, 16, v2
	global_load_dwordx4 v[220:223], v[0:1], off
	s_movk_i32 s0, 0x68
	v_pk_mul_lo_u16 v7, v7, s0 op_sel_hi:[1,0]
	v_lshlrev_b32_e32 v9, 4, v28
	v_and_b32_e32 v8, 0xfff8, v7
	v_lshlrev_b32_e32 v8, 1, v8
	v_add3_u32 v158, s33, v8, v9
	v_mad_i32_i24 v38, v56, -12, v6
	v_lshlrev_b32_e32 v48, 3, v38
	v_ashrrev_i32_e32 v49, 31, v48
	v_lshrrev_b32_e32 v6, 15, v7
	v_and_b32_e32 v6, 0x1fff0, v6
	v_lshlrev_b32_e32 v7, 4, v38
	v_add3_u32 v159, s33, v6, v7
	v_or_b32_e32 v0, v152, v56
	v_mad_i64_i32 v[0:1], s[0:1], v0, s2, v[4:5]
	v_lshl_add_u64 v[0:1], v[48:49], 1, v[0:1]
	global_load_dwordx4 v[224:227], v[0:1], off
	v_or_b32_e32 v0, 0x300, v36
	v_mul_u32_u24_e32 v1, 0x1556, v0
	v_lshrrev_b32_e32 v6, 16, v1
	v_mad_i32_i24 v7, v6, -12, v0
	v_or_b32_e32 v0, v152, v6
	v_lshlrev_b32_e32 v2, 3, v7
	v_mad_i64_i32 v[0:1], s[0:1], v0, s2, v[4:5]
	v_ashrrev_i32_e32 v3, 31, v2
	v_lshl_add_u64 v[0:1], v[2:3], 1, v[0:1]
	global_load_dwordx4 v[228:231], v[0:1], off
	v_mul_u32_u24_e32 v6, 0xd0, v6
	v_lshlrev_b32_e32 v7, 4, v7
	v_add3_u32 v6, s33, v6, v7
	s_waitcnt vmcnt(0)
	ds_write_b128 v157, v[216:219]
	ds_write_b128 v158, v[220:223]
	ds_write_b128 v159, v[224:227]
	ds_write_b128 v6, v[228:231]
	v_or_b32_e32 v0, 0x400, v36
	v_mul_u32_u24_e32 v1, 0x1556, v0
	v_lshrrev_b32_e32 v2, 16, v1
	v_or_b32_e32 v6, 0x500, v36
	v_mad_i32_i24 v9, v2, -12, v0
	v_mul_u32_u24_e32 v3, 0x1556, v6
	v_or_b32_e32 v0, v152, v2
	v_lshlrev_b32_e32 v2, 3, v9
	v_lshrrev_b32_e32 v7, 16, v3
	v_perm_b32 v8, v3, v1, s3
	v_mad_i64_i32 v[0:1], s[0:1], v0, s2, v[4:5]
	v_ashrrev_i32_e32 v3, 31, v2
	v_lshl_add_u64 v[0:1], v[2:3], 1, v[0:1]
	global_load_dwordx4 v[216:219], v[0:1], off
	s_movk_i32 s0, 0xd0
	v_pk_mul_lo_u16 v8, v8, s0 op_sel_hi:[1,0]
	v_lshlrev_b32_e32 v9, 4, v9
	v_and_b32_e32 v10, 0xfff0, v8
	v_add3_u32 v9, s33, v10, v9
	v_mad_i32_i24 v6, v7, -12, v6
	v_or_b32_e32 v0, v152, v7
	v_lshlrev_b32_e32 v2, 3, v6
	v_mad_i64_i32 v[0:1], s[0:1], v0, s2, v[4:5]
	v_ashrrev_i32_e32 v3, 31, v2
	v_lshl_add_u64 v[0:1], v[2:3], 1, v[0:1]
	global_load_dwordx4 v[220:223], v[0:1], off
	v_lshrrev_b32_e32 v4, 16, v8
	v_lshlrev_b32_e32 v5, 4, v6
	v_add3_u32 v4, s33, v4, v5
	s_mov_b64 s[0:1], 0
	s_waitcnt vmcnt(0)
	ds_write_b128 v9, v[216:219]
	ds_write_b128 v4, v[220:223]
	v_and_b32_e32 v0, 7, v54
	v_mov_b32_e32 v1, v36
	s_waitcnt lgkmcnt(0)
	s_barrier
